# staticprio
# baseline (speedup 1.0000x reference)
; #define BAR __builtin_amdgcn_s_barrier()
; #define STAGE4(BROW, BCOL, PN) do { const u16* Ab_ = A + (EPI == EPI_RG ? ((PN) >> 1) * 256 : 0); \
;     STAGE(SB(0, 0), Bt, ldb, (BCOL), 0); STAGE(SA(0, 0), Ab_, lda, (BROW), 0); \
;     STAGE(SB(0, 1), Bt, ldb, (BCOL) + HALF, 0); STAGE(SA(0, 1), Ab_, lda, (BROW) + HALF, 0); } while (0)
; template <int EPI, int lda, int ldb, int N, int K>
; __device__ __forceinline__ void gemm_phase(const u16* __restrict__ A, const u16* __restrict__ Bt, const GemmEpi ep, int wv) {
;     ...
;     const int tidx = otid(wv);
;     if constexpr (!PF) { TILE_COORDS(tile, brow, bcol, pn); STAGE4(brow, bcol, pn); }
;     const int wid = tidx >> 6, lane = tidx & 63, wr = wid >> 2, wc = wid & 3, fr = lane & 15, fq = lane >> 4;
;     const u16* Ab = A + (EPI == EPI_RG ? (pn >> 1) * 256 : 0);
;     f32x4 acc[2][2][4][2] = {};
;     bf16x8 At[4][2], B0[2][2], B1[2][2];
;     constexpr int nt = K / 64;
;     if (wr == 1) BAR;
.LBB0_50:
	v_mbcnt_lo_u32_b32 v0, -1, 0
	v_mbcnt_hi_u32_b32 v0, -1, v0
	s_nop 0
	v_or_b32_e32 v130, s33, v0
	v_ashrrev_i32_e32 v1, 8, v130
	v_cmp_eq_u32_e32 vcc, 1, v1
	s_and_saveexec_b64 s[42:43], vcc
	s_cbranch_execz .LBB0_52
	s_setprio 1
	s_barrier

; #define BAR __builtin_amdgcn_s_barrier()
; #define STAGE4(BROW, BCOL, PN) do { const u16* Ab_ = A + (EPI == EPI_RG ? ((PN) >> 1) * 256 : 0); \
;     STAGE(SB(0, 0), Bt, ldb, (BCOL), 0); STAGE(SA(0, 0), Ab_, lda, (BROW), 0); \
;     STAGE(SB(0, 1), Bt, ldb, (BCOL) + HALF, 0); STAGE(SA(0, 1), Ab_, lda, (BROW) + HALF, 0); } while (0)
; template <int EPI, int lda, int ldb, int N, int K>
; __device__ __forceinline__ void gemm_phase(const u16* __restrict__ A, const u16* __restrict__ Bt, const GemmEpi ep, int wv) {
;     ...
;     const int tidx = otid(wv);
;     if constexpr (!PF) { TILE_COORDS(tile, brow, bcol, pn); STAGE4(brow, bcol, pn); }
;     const int wid = tidx >> 6, lane = tidx & 63, wr = wid >> 2, wc = wid & 3, fr = lane & 15, fq = lane >> 4;
;     const u16* Ab = A + (EPI == EPI_RG ? (pn >> 1) * 256 : 0);
;     f32x4 acc[2][2][4][2] = {};
;     bf16x8 At[4][2], B0[2][2], B1[2][2];
;     constexpr int nt = K / 64;
;     if (wr == 1) BAR;
.LBB0_221:
	v_mbcnt_lo_u32_b32 v0, -1, 0
	v_mbcnt_hi_u32_b32 v0, -1, v0
	s_nop 0
	v_or_b32_e32 v130, s33, v0
	v_ashrrev_i32_e32 v1, 8, v130
	v_cmp_eq_u32_e32 vcc, 1, v1
	s_and_saveexec_b64 s[44:45], vcc
	s_cbranch_execz .LBB0_223
	s_setprio 1
	s_barrier

; #define BAR __builtin_amdgcn_s_barrier()
; #define STAGE4(BROW, BCOL, PN) do { const u16* Ab_ = A + (EPI == EPI_RG ? ((PN) >> 1) * 256 : 0); \
;     STAGE(SB(0, 0), Bt, ldb, (BCOL), 0); STAGE(SA(0, 0), Ab_, lda, (BROW), 0); \
;     STAGE(SB(0, 1), Bt, ldb, (BCOL) + HALF, 0); STAGE(SA(0, 1), Ab_, lda, (BROW) + HALF, 0); } while (0)
; template <int EPI, int lda, int ldb, int N, int K>
; __device__ __forceinline__ void gemm_phase(const u16* __restrict__ A, const u16* __restrict__ Bt, const GemmEpi ep, int wv) {
;     ...
;     const int tidx = otid(wv);
;     if constexpr (!PF) { TILE_COORDS(tile, brow, bcol, pn); STAGE4(brow, bcol, pn); }
;     const int wid = tidx >> 6, lane = tidx & 63, wr = wid >> 2, wc = wid & 3, fr = lane & 15, fq = lane >> 4;
;     const u16* Ab = A + (EPI == EPI_RG ? (pn >> 1) * 256 : 0);
;     f32x4 acc[2][2][4][2] = {};
;     bf16x8 At[4][2], B0[2][2], B1[2][2];
;     constexpr int nt = K / 64;
;     if (wr == 1) BAR;
.LBB0_337:
	v_mbcnt_lo_u32_b32 v0, -1, 0
	v_mbcnt_hi_u32_b32 v0, -1, v0
	s_nop 0
	v_or_b32_e32 v130, s33, v0
	v_ashrrev_i32_e32 v1, 8, v130
	v_cmp_eq_u32_e32 vcc, 1, v1
	s_and_saveexec_b64 s[48:49], vcc
	s_cbranch_execz .LBB0_339
	s_setprio 1
	s_barrier

; #define BAR __builtin_amdgcn_s_barrier()
; #define STAGE4(BROW, BCOL, PN) do { const u16* Ab_ = A + (EPI == EPI_RG ? ((PN) >> 1) * 256 : 0); \
;     STAGE(SB(0, 0), Bt, ldb, (BCOL), 0); STAGE(SA(0, 0), Ab_, lda, (BROW), 0); \
;     STAGE(SB(0, 1), Bt, ldb, (BCOL) + HALF, 0); STAGE(SA(0, 1), Ab_, lda, (BROW) + HALF, 0); } while (0)
; template <int EPI, int lda, int ldb, int N, int K>
; __device__ __forceinline__ void gemm_phase(const u16* __restrict__ A, const u16* __restrict__ Bt, const GemmEpi ep, int wv) {
;     ...
;     const int tidx = otid(wv);
;     if constexpr (!PF) { TILE_COORDS(tile, brow, bcol, pn); STAGE4(brow, bcol, pn); }
;     const int wid = tidx >> 6, lane = tidx & 63, wr = wid >> 2, wc = wid & 3, fr = lane & 15, fq = lane >> 4;
;     const u16* Ab = A + (EPI == EPI_RG ? (pn >> 1) * 256 : 0);
;     f32x4 acc[2][2][4][2] = {};
;     bf16x8 At[4][2], B0[2][2], B1[2][2];
;     constexpr int nt = K / 64;
;     if (wr == 1) BAR;
.LBB0_651:
	v_mbcnt_lo_u32_b32 v0, -1, 0
	v_mbcnt_hi_u32_b32 v0, -1, v0
	s_nop 0
	v_or_b32_e32 v130, s33, v0
	v_ashrrev_i32_e32 v1, 8, v130
	v_cmp_eq_u32_e32 vcc, 1, v1
	s_and_saveexec_b64 s[52:53], vcc
	s_cbranch_execz .LBB0_653
	s_setprio 1
	s_barrier

; #define BAR __builtin_amdgcn_s_barrier()
; #define STAGE4(BROW, BCOL, PN) do { const u16* Ab_ = A + (EPI == EPI_RG ? ((PN) >> 1) * 256 : 0); \
;     STAGE(SB(0, 0), Bt, ldb, (BCOL), 0); STAGE(SA(0, 0), Ab_, lda, (BROW), 0); \
;     STAGE(SB(0, 1), Bt, ldb, (BCOL) + HALF, 0); STAGE(SA(0, 1), Ab_, lda, (BROW) + HALF, 0); } while (0)
; template <int EPI, int lda, int ldb, int N, int K>
; __device__ __forceinline__ void gemm_phase(const u16* __restrict__ A, const u16* __restrict__ Bt, const GemmEpi ep, int wv) {
;     ...
;     const int tidx = otid(wv);
;     if constexpr (!PF) { TILE_COORDS(tile, brow, bcol, pn); STAGE4(brow, bcol, pn); }
;     const int wid = tidx >> 6, lane = tidx & 63, wr = wid >> 2, wc = wid & 3, fr = lane & 15, fq = lane >> 4;
;     const u16* Ab = A + (EPI == EPI_RG ? (pn >> 1) * 256 : 0);
;     f32x4 acc[2][2][4][2] = {};
;     bf16x8 At[4][2], B0[2][2], B1[2][2];
;     constexpr int nt = K / 64;
;     if (wr == 1) BAR;
.LBB0_767:
	v_mbcnt_lo_u32_b32 v0, -1, 0
	v_mbcnt_hi_u32_b32 v0, -1, v0
	s_nop 0
	v_or_b32_e32 v130, s33, v0
	v_ashrrev_i32_e32 v1, 8, v130
	v_cmp_eq_u32_e32 vcc, 1, v1
	s_and_saveexec_b64 s[50:51], vcc
	s_cbranch_execz .LBB0_769
	s_setprio 1
	s_barrier

; #define BAR __builtin_amdgcn_s_barrier()
; #define STAGE4(BROW, BCOL, PN) do { const u16* Ab_ = A + (EPI == EPI_RG ? ((PN) >> 1) * 256 : 0); \
;     STAGE(SB(0, 0), Bt, ldb, (BCOL), 0); STAGE(SA(0, 0), Ab_, lda, (BROW), 0); \
;     STAGE(SB(0, 1), Bt, ldb, (BCOL) + HALF, 0); STAGE(SA(0, 1), Ab_, lda, (BROW) + HALF, 0); } while (0)
; template <int EPI, int lda, int ldb, int N, int K>
; __device__ __forceinline__ void gemm_phase(const u16* __restrict__ A, const u16* __restrict__ Bt, const GemmEpi ep, int wv) {
;     ...
;     const int tidx = otid(wv);
;     if constexpr (!PF) { TILE_COORDS(tile, brow, bcol, pn); STAGE4(brow, bcol, pn); }
;     const int wid = tidx >> 6, lane = tidx & 63, wr = wid >> 2, wc = wid & 3, fr = lane & 15, fq = lane >> 4;
;     const u16* Ab = A + (EPI == EPI_RG ? (pn >> 1) * 256 : 0);
;     f32x4 acc[2][2][4][2] = {};
;     bf16x8 At[4][2], B0[2][2], B1[2][2];
;     constexpr int nt = K / 64;
;     if (wr == 1) BAR;
.LBB0_1144:
	v_mbcnt_lo_u32_b32 v0, -1, 0
	v_mbcnt_hi_u32_b32 v0, -1, v0
	s_nop 0
	v_or_b32_e32 v130, s33, v0
	v_ashrrev_i32_e32 v1, 8, v130
	v_cmp_eq_u32_e32 vcc, 1, v1
	s_and_saveexec_b64 s[60:61], vcc
	s_cbranch_execz .LBB0_1146
	s_setprio 1
	s_barrier

; #define BAR __builtin_amdgcn_s_barrier()
; #define STAGE4(BROW, BCOL, PN) do { const u16* Ab_ = A + (EPI == EPI_RG ? ((PN) >> 1) * 256 : 0); \
;     STAGE(SB(0, 0), Bt, ldb, (BCOL), 0); STAGE(SA(0, 0), Ab_, lda, (BROW), 0); \
;     STAGE(SB(0, 1), Bt, ldb, (BCOL) + HALF, 0); STAGE(SA(0, 1), Ab_, lda, (BROW) + HALF, 0); } while (0)
; template <int EPI, int lda, int ldb, int N, int K>
; __device__ __forceinline__ void gemm_phase(const u16* __restrict__ A, const u16* __restrict__ Bt, const GemmEpi ep, int wv) {
;     ...
;     const int tidx = otid(wv);
;     if constexpr (!PF) { TILE_COORDS(tile, brow, bcol, pn); STAGE4(brow, bcol, pn); }
;     const int wid = tidx >> 6, lane = tidx & 63, wr = wid >> 2, wc = wid & 3, fr = lane & 15, fq = lane >> 4;
;     const u16* Ab = A + (EPI == EPI_RG ? (pn >> 1) * 256 : 0);
;     f32x4 acc[2][2][4][2] = {};
;     bf16x8 At[4][2], B0[2][2], B1[2][2];
;     constexpr int nt = K / 64;
;     if (wr == 1) BAR;
.LBB0_1561:
	v_mbcnt_lo_u32_b32 v0, -1, 0
	v_mbcnt_hi_u32_b32 v0, -1, v0
	s_nop 0
	v_or_b32_e32 v130, s33, v0
	v_ashrrev_i32_e32 v1, 8, v130
	v_cmp_eq_u32_e32 vcc, 1, v1
	s_and_saveexec_b64 s[40:41], vcc
	s_cbranch_execz .LBB0_1563
	s_setprio 1
	s_barrier

; #define BAR __builtin_amdgcn_s_barrier()
; #define STAGE4(BROW, BCOL, PN) do { const u16* Ab_ = A + (EPI == EPI_RG ? ((PN) >> 1) * 256 : 0); \
;     STAGE(SB(0, 0), Bt, ldb, (BCOL), 0); STAGE(SA(0, 0), Ab_, lda, (BROW), 0); \
;     STAGE(SB(0, 1), Bt, ldb, (BCOL) + HALF, 0); STAGE(SA(0, 1), Ab_, lda, (BROW) + HALF, 0); } while (0)
; template <int EPI, int lda, int ldb, int N, int K>
; __device__ __forceinline__ void gemm_phase(const u16* __restrict__ A, const u16* __restrict__ Bt, const GemmEpi ep, int wv) {
;     ...
;     const int tidx = otid(wv);
;     if constexpr (!PF) { TILE_COORDS(tile, brow, bcol, pn); STAGE4(brow, bcol, pn); }
;     const int wid = tidx >> 6, lane = tidx & 63, wr = wid >> 2, wc = wid & 3, fr = lane & 15, fq = lane >> 4;
;     const u16* Ab = A + (EPI == EPI_RG ? (pn >> 1) * 256 : 0);
;     f32x4 acc[2][2][4][2] = {};
;     bf16x8 At[4][2], B0[2][2], B1[2][2];
;     constexpr int nt = K / 64;
;     if (wr == 1) BAR;
.LBB0_1621:
	v_mbcnt_lo_u32_b32 v0, -1, 0
	v_mbcnt_hi_u32_b32 v0, -1, v0
	s_nop 0
	v_or_b32_e32 v147, s33, v0
	v_ashrrev_i32_e32 v1, 8, v147
	v_cmp_eq_u32_e32 vcc, 1, v1
	s_and_saveexec_b64 s[28:29], vcc
	s_cbranch_execz .LBB0_1623
	s_setprio 1
	s_barrier
